# fft_stage1 and fft_stage2 f_to_lds round trips batched (4 and 8 loads issued together)
# speedup vs baseline: 1.0546x; 1.0012x over previous
.LBB0_329:
	s_cmp_lt_u32 s62, 16
	s_cbranch_scc1 .LBB0_335
	s_mov_b64 s[0:1], s[60:61]
	v_mbcnt_lo_u32_b32 v0, -1, 0
	v_mbcnt_hi_u32_b32 v0, -1, v0
	s_movk_i32 s2, 0x800
	v_or_b32_e32 v1, s68, v0
	s_load_dwordx2 s[0:1], s[0:1], 0xc0
	v_readfirstlane_b32 s8, v1
	v_cmp_gt_i32_e32 vcc, s2, v1
	s_waitcnt lgkmcnt(0)
	s_and_saveexec_b64 s[2:3], vcc
	s_cbranch_execz .LBB0_332
	s_add_u32 s4, s0, 0x180000
	s_addc_u32 s5, s1, 0
	v_lshlrev_b32_e32 v2, 4, v1
	v_lshrrev_b32_e32 v3, 4, v1
	v_lshl_add_u32 v3, v3, 4, v2
	s_movk_i32 s9, 0x5ff
	s_mov_b64 s[6:7], exec
	global_load_dwordx4 v[4:7], v2, s[4:5]
	s_add_u32 s4, s4, 0x2000
	s_addc_u32 s5, s5, 0
	global_load_dwordx4 v[8:11], v2, s[4:5]
	s_add_u32 s4, s4, 0x2000
	s_addc_u32 s5, s5, 0
	global_load_dwordx4 v[12:15], v2, s[4:5]
	s_add_u32 s4, s4, 0x2000
	s_addc_u32 s5, s5, 0
	global_load_dwordx4 v[16:19], v2, s[4:5]
	s_waitcnt vmcnt(3)
	ds_write_b128 v3, v[4:7]
	s_waitcnt vmcnt(2)
	ds_write_b128 v3, v[8:11] offset:8704
	s_waitcnt vmcnt(1)
	ds_write_b128 v3, v[12:15] offset:17408
	s_waitcnt vmcnt(0)
	ds_write_b128 v3, v[16:19] offset:26112

.LBB0_384:
	s_or_b64 exec, exec, s[34:35]
	s_mov_b64 s[0:1], s[60:61]
	s_waitcnt lgkmcnt(0)
	s_barrier
	v_mbcnt_lo_u32_b32 v0, -1, 0
	v_mbcnt_hi_u32_b32 v0, -1, v0
	s_load_dwordx2 s[0:1], s[0:1], 0xc0
	v_or_b32_e32 v1, s68, v0
	v_cmp_gt_i32_e32 vcc, s33, v1
	v_readfirstlane_b32 s10, v1
	s_waitcnt lgkmcnt(0)
	s_and_saveexec_b64 s[2:3], vcc
	s_cbranch_execz .LBB0_387
	s_add_u32 s6, s0, 0x188000
	s_addc_u32 s7, s1, 0
	v_lshlrev_b32_e32 v2, 4, v1
	v_lshrrev_b32_e32 v3, 5, v1
	v_lshl_add_u32 v3, v3, 4, v2
	s_movk_i32 s11, 0xdff
	s_mov_b64 s[8:9], exec
	global_load_dwordx4 v[4:7], v2, s[6:7]
	s_add_u32 s6, s6, 0x2000
	s_addc_u32 s7, s7, 0
	global_load_dwordx4 v[8:11], v2, s[6:7]
	s_add_u32 s6, s6, 0x2000
	s_addc_u32 s7, s7, 0
	global_load_dwordx4 v[12:15], v2, s[6:7]
	s_add_u32 s6, s6, 0x2000
	s_addc_u32 s7, s7, 0
	global_load_dwordx4 v[16:19], v2, s[6:7]
	s_add_u32 s6, s6, 0x2000
	s_addc_u32 s7, s7, 0
	global_load_dwordx4 v[20:23], v2, s[6:7]
	s_add_u32 s6, s6, 0x2000
	s_addc_u32 s7, s7, 0
	global_load_dwordx4 v[24:27], v2, s[6:7]
	s_add_u32 s6, s6, 0x2000
	s_addc_u32 s7, s7, 0
	global_load_dwordx4 v[28:31], v2, s[6:7]
	s_add_u32 s6, s6, 0x2000
	s_addc_u32 s7, s7, 0
	global_load_dwordx4 v[32:35], v2, s[6:7]
	s_waitcnt vmcnt(7)
	ds_write_b128 v3, v[4:7]
	s_waitcnt vmcnt(6)
	ds_write_b128 v3, v[8:11] offset:8448
	s_waitcnt vmcnt(5)
	ds_write_b128 v3, v[12:15] offset:16896
	s_waitcnt vmcnt(4)
	ds_write_b128 v3, v[16:19] offset:25344
	s_waitcnt vmcnt(3)
	ds_write_b128 v3, v[20:23] offset:33792
	s_waitcnt vmcnt(2)
	ds_write_b128 v3, v[24:27] offset:42240
	s_waitcnt vmcnt(1)
	ds_write_b128 v3, v[28:31] offset:50688
	s_waitcnt vmcnt(0)
	ds_write_b128 v3, v[32:35] offset:59136
